# flash loops: rescale-needed test shortened to two compares plus SALU or (no EXEC round trip, no mask re-derivation)
# speedup vs baseline: 1.0024x; 1.0024x over previous
; DI float fexp2(float x) { return __builtin_amdgcn_exp2f(x); }
; DI float xhalf_max(float v) { auto rr = __builtin_amdgcn_permlane32_swap(__float_as_uint(v), __float_as_uint(v), false, false); return fmaxf(__uint_as_float(rr[0]), __uint_as_float(rr[1])); }
; template <int DQK, int MODE, class Mask> ...
;     ...
;                 asm volatile("s_nop 15\n\ts_nop 7" : "+v"(s[0]), "+v"(s[1]));
;                 float mt, mu;
;                 asm volatile("v_max3_f32 %0, %1, %2, %3" : "=v"(mt) : "v"(s[0][0]), "v"(s[0][1]), "v"(s[0][2]));
;                 asm volatile("v_max3_f32 %0, %1, %2, %3" : "=v"(mu) : "v"(s[1][0]), "v"(s[1][1]), "v"(s[1][2]));
; #pragma unroll
;                 for (int i = 3; i < 15; i += 2) {
;                     asm volatile("v_max3_f32 %0, %1, %2, %3" : "=v"(mt) : "v"(mt), "v"(s[0][i]), "v"(s[0][i + 1]));
;                     asm volatile("v_max3_f32 %0, %1, %2, %3" : "=v"(mu) : "v"(mu), "v"(s[1][i]), "v"(s[1][i + 1]));
;                 }
;                 asm volatile("v_max3_f32 %0, %1, %2, %3" : "=v"(mt) : "v"(mt), "v"(s[0][15]), "v"(s[1][15]));
;                 asm volatile("v_max_f32 %0, %1, %2" : "=v"(mt) : "v"(mt), "v"(mu));
;                 mt = on ? mt : -3e30f;
;                 mt = xhalf_max(mt);
;                 const bool need = (mt > 8.0f) || (!href && mt > -1e29f);
;                 if (__builtin_amdgcn_ballot_w64(need) != 0ull) {
;                     const float dl = need ? mt : 0.f;
;                     const float alpha = href ? fexp2(-dl) : 0.f;
;                     mref += dl; href = href || need;
; #pragma unroll
;                     for (int kb = 0; kb < 2; ++kb)
; #pragma unroll
;                         for (int i = 0; i < 16; ++i) s[kb][i] -= dl;
; #pragma unroll
;                     for (int i = 0; i < 16; ++i) { negm16[i] = -mref; ol[i] *= alpha; }
;                     if (MODE == 0) {
; #pragma unroll
;                         for (int d = 0; d < 2; ++d)
; #pragma unroll
;                             for (int i = 0; i < 16; ++i) o[d][i] *= alpha;
;                     }
;                 }
.LBB0_1017:
	s_nop 15
	s_nop 7
	s_mov_b64 s[12:13], -1
	v_max3_f32 v217, v82, v83, v84
	v_max3_f32 v219, v66, v67, v68
	s_nop 0
	v_max3_f32 v217, v217, v85, v86
	v_max3_f32 v219, v219, v69, v70
	s_nop 0
	v_max3_f32 v217, v217, v87, v88
	v_max3_f32 v219, v219, v71, v72
	s_nop 0
	v_max3_f32 v217, v217, v89, v90
	v_max3_f32 v219, v219, v73, v74
	s_nop 0
	v_max3_f32 v217, v217, v91, v92
	v_max3_f32 v219, v219, v75, v76
	s_nop 0
	v_max3_f32 v217, v217, v93, v94
	v_max3_f32 v219, v219, v77, v78
	s_nop 0
	v_max3_f32 v217, v217, v95, v96
	v_max3_f32 v219, v219, v79, v80
	s_nop 0
	v_max3_f32 v217, v217, v97, v81
	s_nop 0
	v_max_f32 v217, v217, v219
	s_nop 0
	v_mov_b32_e32 v219, v217
	s_nop 1
	v_permlane32_swap_b32_e32 v217, v219
	v_max_f32_e32 v219, v219, v219
	v_max_f32_e32 v217, v217, v217
	v_max_f32_e32 v217, v217, v219
	v_cmp_lt_f32_e32 vcc, s60, v217
	v_cmp_lt_f32_e64 s[16:17], s61, v217
	s_andn2_b64 s[16:17], s[16:17], s[6:7]
	s_or_b64 s[12:13], vcc, s[16:17]
	s_cbranch_scc0 .LBB0_1021
	v_cndmask_b32_e64 v50, 0, v217, s[12:13]
	v_exp_f32_e64 v51, -v50
	v_add_f32_e32 v191, v191, v50
	s_or_b64 s[12:13], s[6:7], s[12:13]
	v_sub_f32_e32 v82, v82, v50
	v_sub_f32_e32 v83, v83, v50
	v_sub_f32_e32 v84, v84, v50
	v_cndmask_b32_e64 v52, 0, v51, s[6:7]
	v_sub_f32_e32 v85, v85, v50
	v_sub_f32_e32 v86, v86, v50
	v_sub_f32_e32 v87, v87, v50
	v_sub_f32_e32 v88, v88, v50
	v_sub_f32_e32 v89, v89, v50
	v_sub_f32_e32 v90, v90, v50
	v_sub_f32_e32 v91, v91, v50
	v_sub_f32_e32 v92, v92, v50
	v_sub_f32_e32 v93, v93, v50
	v_sub_f32_e32 v94, v94, v50
	v_sub_f32_e32 v95, v95, v50
	v_sub_f32_e32 v96, v96, v50
	v_sub_f32_e32 v97, v97, v50
	v_sub_f32_e32 v66, v66, v50
	v_sub_f32_e32 v67, v67, v50
	v_sub_f32_e32 v68, v68, v50
	v_sub_f32_e32 v69, v69, v50
	v_sub_f32_e32 v70, v70, v50
	v_sub_f32_e32 v71, v71, v50
	v_sub_f32_e32 v72, v72, v50
	v_sub_f32_e32 v73, v73, v50
	v_sub_f32_e32 v74, v74, v50
	v_sub_f32_e32 v75, v75, v50
	v_sub_f32_e32 v76, v76, v50
	v_sub_f32_e32 v77, v77, v50
	v_sub_f32_e32 v78, v78, v50
	v_sub_f32_e32 v79, v79, v50
	v_sub_f32_e32 v80, v80, v50
	v_sub_f32_e32 v81, v81, v50
	v_xor_b32_e32 v50, 0x80000000, v191
	s_andn2_b64 s[6:7], s[6:7], exec
	s_and_b64 s[12:13], s[12:13], exec
	v_pk_mul_f32 v[48:49], v[48:49], v[52:53] op_sel_hi:[1,0]
	v_pk_mul_f32 v[46:47], v[46:47], v[52:53] op_sel_hi:[1,0]
	v_pk_mul_f32 v[44:45], v[44:45], v[52:53] op_sel_hi:[1,0]
	v_pk_mul_f32 v[42:43], v[42:43], v[52:53] op_sel_hi:[1,0]
	v_pk_mul_f32 v[40:41], v[40:41], v[52:53] op_sel_hi:[1,0]
	v_pk_mul_f32 v[38:39], v[38:39], v[52:53] op_sel_hi:[1,0]
	v_pk_mul_f32 v[36:37], v[36:37], v[52:53] op_sel_hi:[1,0]
	v_pk_mul_f32 v[34:35], v[34:35], v[52:53] op_sel_hi:[1,0]
	v_pk_mul_f32 v[16:17], v[16:17], v[52:53] op_sel_hi:[1,0]
	v_pk_mul_f32 v[14:15], v[14:15], v[52:53] op_sel_hi:[1,0]
	v_pk_mul_f32 v[12:13], v[12:13], v[52:53] op_sel_hi:[1,0]
	v_pk_mul_f32 v[10:11], v[10:11], v[52:53] op_sel_hi:[1,0]
	v_pk_mul_f32 v[8:9], v[8:9], v[52:53] op_sel_hi:[1,0]
	v_pk_mul_f32 v[6:7], v[6:7], v[52:53] op_sel_hi:[1,0]
	v_pk_mul_f32 v[4:5], v[4:5], v[52:53] op_sel_hi:[1,0]
	v_pk_mul_f32 v[2:3], v[2:3], v[52:53] op_sel_hi:[1,0]
	v_pk_mul_f32 v[32:33], v[32:33], v[52:53] op_sel_hi:[1,0]
	v_pk_mul_f32 v[30:31], v[30:31], v[52:53] op_sel_hi:[1,0]
	v_pk_mul_f32 v[28:29], v[28:29], v[52:53] op_sel_hi:[1,0]
	v_pk_mul_f32 v[26:27], v[26:27], v[52:53] op_sel_hi:[1,0]
	v_pk_mul_f32 v[24:25], v[24:25], v[52:53] op_sel_hi:[1,0]
	v_pk_mul_f32 v[22:23], v[22:23], v[52:53] op_sel_hi:[1,0]
	v_pk_mul_f32 v[20:21], v[20:21], v[52:53] op_sel_hi:[1,0]
	v_pk_mul_f32 v[18:19], v[18:19], v[52:53] op_sel_hi:[1,0]
	s_or_b64 s[6:7], s[6:7], s[12:13]
	v_mov_b32_e32 v51, v50
	v_mov_b32_e32 v52, v50
	v_mov_b32_e32 v53, v50
	v_mov_b32_e32 v54, v50
	v_mov_b32_e32 v55, v50
	v_mov_b32_e32 v56, v50
	v_mov_b32_e32 v57, v50
	v_mov_b32_e32 v58, v50
	v_mov_b32_e32 v59, v50
	v_mov_b32_e32 v60, v50
	v_mov_b32_e32 v61, v50
	v_mov_b32_e32 v62, v50
	v_mov_b32_e32 v63, v50
	v_mov_b32_e32 v64, v50
	v_mov_b32_e32 v65, v50

; DI float fexp2(float x) { return __builtin_amdgcn_exp2f(x); }
; DI float xhalf_max(float v) { auto rr = __builtin_amdgcn_permlane32_swap(__float_as_uint(v), __float_as_uint(v), false, false); return fmaxf(__uint_as_float(rr[0]), __uint_as_float(rr[1])); }
; template <int DQK, int MODE, class Mask> ...
;     ...
;                 asm volatile("s_nop 15\n\ts_nop 7" : "+v"(s[0]), "+v"(s[1]));
;                 float mt, mu;
;                 asm volatile("v_max3_f32 %0, %1, %2, %3" : "=v"(mt) : "v"(s[0][0]), "v"(s[0][1]), "v"(s[0][2]));
;                 asm volatile("v_max3_f32 %0, %1, %2, %3" : "=v"(mu) : "v"(s[1][0]), "v"(s[1][1]), "v"(s[1][2]));
; #pragma unroll
;                 for (int i = 3; i < 15; i += 2) {
;                     asm volatile("v_max3_f32 %0, %1, %2, %3" : "=v"(mt) : "v"(mt), "v"(s[0][i]), "v"(s[0][i + 1]));
;                     asm volatile("v_max3_f32 %0, %1, %2, %3" : "=v"(mu) : "v"(mu), "v"(s[1][i]), "v"(s[1][i + 1]));
;                 }
;                 asm volatile("v_max3_f32 %0, %1, %2, %3" : "=v"(mt) : "v"(mt), "v"(s[0][15]), "v"(s[1][15]));
;                 asm volatile("v_max_f32 %0, %1, %2" : "=v"(mt) : "v"(mt), "v"(mu));
;                 mt = on ? mt : -3e30f;
;                 mt = xhalf_max(mt);
;                 const bool need = (mt > 8.0f) || (!href && mt > -1e29f);
;                 if (__builtin_amdgcn_ballot_w64(need) != 0ull) {
;                     const float dl = need ? mt : 0.f;
;                     const float alpha = href ? fexp2(-dl) : 0.f;
;                     mref += dl; href = href || need;
; #pragma unroll
;                     for (int kb = 0; kb < 2; ++kb)
; #pragma unroll
;                         for (int i = 0; i < 16; ++i) s[kb][i] -= dl;
; #pragma unroll
;                     for (int i = 0; i < 16; ++i) { negm16[i] = -mref; ol[i] *= alpha; }
;                     if (MODE == 0) {
; #pragma unroll
;                         for (int d = 0; d < 2; ++d)
; #pragma unroll
;                             for (int i = 0; i < 16; ++i) o[d][i] *= alpha;
;                     }
;                 }
.LBB0_1051:
	s_nop 15
	s_nop 7
	s_mov_b64 s[12:13], -1
	v_max3_f32 v0, v82, v83, v84
	v_max3_f32 v203, v66, v67, v68
	s_nop 0
	v_max3_f32 v0, v0, v85, v86
	v_max3_f32 v203, v203, v69, v70
	s_nop 0
	v_max3_f32 v0, v0, v87, v88
	v_max3_f32 v203, v203, v71, v72
	s_nop 0
	v_max3_f32 v0, v0, v89, v90
	v_max3_f32 v203, v203, v73, v74
	s_nop 0
	v_max3_f32 v0, v0, v91, v92
	v_max3_f32 v203, v203, v75, v76
	s_nop 0
	v_max3_f32 v0, v0, v93, v94
	v_max3_f32 v203, v203, v77, v78
	s_nop 0
	v_max3_f32 v0, v0, v95, v96
	v_max3_f32 v203, v203, v79, v80
	s_nop 0
	v_max3_f32 v0, v0, v97, v81
	s_nop 0
	v_max_f32 v0, v0, v203
	s_nop 0
	v_mov_b32_e32 v203, v0
	s_nop 1
	v_permlane32_swap_b32_e32 v0, v203
	v_max_f32_e32 v203, v203, v203
	v_max_f32_e32 v0, v0, v0
	v_max_f32_e32 v0, v0, v203
	v_cmp_lt_f32_e32 vcc, s60, v0
	v_cmp_lt_f32_e64 s[16:17], s61, v0
	s_andn2_b64 s[16:17], s[16:17], s[6:7]
	s_or_b64 s[12:13], vcc, s[16:17]
	s_cbranch_scc0 .LBB0_1055
	v_cndmask_b32_e64 v50, 0, v0, s[12:13]
	v_exp_f32_e64 v0, -v50
	v_add_f32_e32 v191, v191, v50
	s_or_b64 s[12:13], s[6:7], s[12:13]
	v_sub_f32_e32 v82, v82, v50
	v_sub_f32_e32 v83, v83, v50
	v_sub_f32_e32 v84, v84, v50
	v_cndmask_b32_e64 v0, 0, v0, s[6:7]
	v_sub_f32_e32 v85, v85, v50
	v_sub_f32_e32 v86, v86, v50
	v_sub_f32_e32 v87, v87, v50
	v_sub_f32_e32 v88, v88, v50
	v_sub_f32_e32 v89, v89, v50
	v_sub_f32_e32 v90, v90, v50
	v_sub_f32_e32 v91, v91, v50
	v_sub_f32_e32 v92, v92, v50
	v_sub_f32_e32 v93, v93, v50
	v_sub_f32_e32 v94, v94, v50
	v_sub_f32_e32 v95, v95, v50
	v_sub_f32_e32 v96, v96, v50
	v_sub_f32_e32 v97, v97, v50
	v_sub_f32_e32 v66, v66, v50
	v_sub_f32_e32 v67, v67, v50
	v_sub_f32_e32 v68, v68, v50
	v_sub_f32_e32 v69, v69, v50
	v_sub_f32_e32 v70, v70, v50
	v_sub_f32_e32 v71, v71, v50
	v_sub_f32_e32 v72, v72, v50
	v_sub_f32_e32 v73, v73, v50
	v_sub_f32_e32 v74, v74, v50
	v_sub_f32_e32 v75, v75, v50
	v_sub_f32_e32 v76, v76, v50
	v_sub_f32_e32 v77, v77, v50
	v_sub_f32_e32 v78, v78, v50
	v_sub_f32_e32 v79, v79, v50
	v_sub_f32_e32 v80, v80, v50
	v_sub_f32_e32 v81, v81, v50
	v_xor_b32_e32 v50, 0x80000000, v191
	s_andn2_b64 s[6:7], s[6:7], exec
	s_and_b64 s[12:13], s[12:13], exec
	v_pk_mul_f32 v[48:49], v[48:49], v[0:1] op_sel_hi:[1,0]
	v_pk_mul_f32 v[46:47], v[46:47], v[0:1] op_sel_hi:[1,0]
	v_pk_mul_f32 v[44:45], v[44:45], v[0:1] op_sel_hi:[1,0]
	v_pk_mul_f32 v[42:43], v[42:43], v[0:1] op_sel_hi:[1,0]
	v_pk_mul_f32 v[40:41], v[40:41], v[0:1] op_sel_hi:[1,0]
	v_pk_mul_f32 v[38:39], v[38:39], v[0:1] op_sel_hi:[1,0]
	v_pk_mul_f32 v[36:37], v[36:37], v[0:1] op_sel_hi:[1,0]
	v_pk_mul_f32 v[34:35], v[34:35], v[0:1] op_sel_hi:[1,0]
	v_pk_mul_f32 v[16:17], v[16:17], v[0:1] op_sel_hi:[1,0]
	v_pk_mul_f32 v[14:15], v[14:15], v[0:1] op_sel_hi:[1,0]
	v_pk_mul_f32 v[12:13], v[12:13], v[0:1] op_sel_hi:[1,0]
	v_pk_mul_f32 v[10:11], v[10:11], v[0:1] op_sel_hi:[1,0]
	v_pk_mul_f32 v[8:9], v[8:9], v[0:1] op_sel_hi:[1,0]
	v_pk_mul_f32 v[6:7], v[6:7], v[0:1] op_sel_hi:[1,0]
	v_pk_mul_f32 v[4:5], v[4:5], v[0:1] op_sel_hi:[1,0]
	v_pk_mul_f32 v[2:3], v[2:3], v[0:1] op_sel_hi:[1,0]
	v_pk_mul_f32 v[32:33], v[32:33], v[0:1] op_sel_hi:[1,0]
	v_pk_mul_f32 v[30:31], v[30:31], v[0:1] op_sel_hi:[1,0]
	v_pk_mul_f32 v[28:29], v[28:29], v[0:1] op_sel_hi:[1,0]
	v_pk_mul_f32 v[26:27], v[26:27], v[0:1] op_sel_hi:[1,0]
	v_pk_mul_f32 v[24:25], v[24:25], v[0:1] op_sel_hi:[1,0]
	v_pk_mul_f32 v[22:23], v[22:23], v[0:1] op_sel_hi:[1,0]
	v_pk_mul_f32 v[20:21], v[20:21], v[0:1] op_sel_hi:[1,0]
	v_pk_mul_f32 v[18:19], v[18:19], v[0:1] op_sel_hi:[1,0]
	s_or_b64 s[6:7], s[6:7], s[12:13]
	v_mov_b32_e32 v51, v50
	v_mov_b32_e32 v52, v50
	v_mov_b32_e32 v53, v50
	v_mov_b32_e32 v54, v50
	v_mov_b32_e32 v55, v50
	v_mov_b32_e32 v56, v50
	v_mov_b32_e32 v57, v50
	v_mov_b32_e32 v58, v50
	v_mov_b32_e32 v59, v50
	v_mov_b32_e32 v60, v50
	v_mov_b32_e32 v61, v50
	v_mov_b32_e32 v62, v50
	v_mov_b32_e32 v63, v50
	v_mov_b32_e32 v64, v50
	v_mov_b32_e32 v65, v50

; template <int DQK, int MODE, class Mask> ...
;     ...
;                 for (int kk = 0; kk < NKS; ++kk) kf[kb][kk] = *(const LAS bf16x8*)(Ks + (32 * kb + r) * KP + (16 * kk + 8 * h) * 2);
;             __builtin_amdgcn_sched_barrier(0);
;             f32x16 s[2];
;             asm volatile("v_mfma_f32_32x32x16_bf16 %0, %1, %2, %3" : "=&v"(s[0]) : "v"(kf[0][0]), "v"(qf[0]), "v"(negm16));
;             asm volatile("v_mfma_f32_32x32x16_bf16 %0, %1, %2, %3" : "=&v"(s[1]) : "v"(kf[1][0]), "v"(qf[0]), "v"(negm16));
; #pragma unroll
;             for (int kk = 1; kk < NKS; ++kk) {
;                 s[0] = MFMA32(kf[0][kk], qf[kk], s[0]);
;                 s[1] = MFMA32(kf[1][kk], qf[kk], s[1]);
;             }
;             __builtin_amdgcn_sched_barrier(0);
;             s16x4 vlo[2][2][2], vhi[2][2][2];
;             if (MODE != 1) {
;                 const int q4 = (lane & 15) >> 2, p4 = lane & 3, blk = (lane >> 4) & 1;
;                 const LAS char* vb0 = Vs + (4 * h + q4) * VP + (16 * blk) * 2 + 8 * p4;
; #pragma unroll
;                 for (int kb = 0; kb < 2; ++kb)
; #pragma unroll
;                     for (int s2 = 0; s2 < 2; ++s2)
; #pragma unroll
;                         for (int d = 0; d < 2; ++d) { const LAS char* vb = vb0 + (32 * kb + 16 * s2) * VP + (32 * d) * 2; vlo[kb][s2][d] = vtr(vb); vhi[kb][s2][d] = vtr(vb + 8 * VP); }
;             }
;             __builtin_amdgcn_sched_barrier(0);
;             const int key0 = j * 64 + 4 * h;
;             if (mask.needs(j)) {
; #pragma unroll
;                 for (int kb = 0; kb < 2; ++kb)
; #pragma unroll
;                     for (int i = 0; i < 16; ++i) { const int key = key0 + 32 * kb + (i & 3) + 8 * (i >> 2); s[kb][i] = mask(key, j) ? s[kb][i] : -3e30f; }
;             }
;             const bool on = mask.lane_on(j);
;             if (MODE == 0 || MODE == 1) {
;                 asm volatile("s_nop 15\n\ts_nop 7" : "+v"(s[0]), "+v"(s[1]));
;                 float mt, mu;
;                 asm volatile("v_max3_f32 %0, %1, %2, %3" : "=v"(mt) : "v"(s[0][0]), "v"(s[0][1]), "v"(s[0][2]));
;                 asm volatile("v_max3_f32 %0, %1, %2, %3" : "=v"(mu) : "v"(s[1][0]), "v"(s[1][1]), "v"(s[1][2]));
; #pragma unroll
;                 for (int i = 3; i < 15; i += 2) {
;                     asm volatile("v_max3_f32 %0, %1, %2, %3" : "=v"(mt) : "v"(mt), "v"(s[0][i]), "v"(s[0][i + 1]));
.LBB0_1067:
	s_mulk_i32 s18, 0x3400
	v_add_u32_e32 v0, s18, v219
	v_add_u32_e32 v34, v0, v224
	v_add_u32_e32 v0, v0, v225
	ds_read_b128 v[50:53], v34
	ds_read_b128 v[54:57], v34 offset:32
	ds_read_b128 v[76:79], v34 offset:64
	ds_read_b128 v[80:83], v34 offset:96
	ds_read_b128 v[84:87], v0
	ds_read_b128 v[88:91], v0 offset:32
	ds_read_b128 v[92:95], v0 offset:64
	ds_read_b128 v[114:117], v0 offset:96
	s_waitcnt lgkmcnt(7)
	v_mfma_f32_32x32x16_bf16 v[34:49], v[50:53], v[98:101], v[18:33]
	s_waitcnt lgkmcnt(6)
	v_mfma_f32_32x32x16_bf16 v[34:49], v[54:57], v[102:105], v[34:49]
	s_waitcnt lgkmcnt(3)
	v_mfma_f32_32x32x16_bf16 v[50:65], v[84:87], v[98:101], v[18:33]
	s_waitcnt lgkmcnt(2)
	v_mfma_f32_32x32x16_bf16 v[50:65], v[88:91], v[102:105], v[50:65]
	v_mfma_f32_32x32x16_bf16 v[34:49], v[76:79], v[106:109], v[34:49]
	s_waitcnt lgkmcnt(1)
	v_mfma_f32_32x32x16_bf16 v[50:65], v[92:95], v[106:109], v[50:65]
	v_mfma_f32_32x32x16_bf16 v[34:49], v[80:83], v[110:113], v[34:49]
	s_waitcnt lgkmcnt(0)
	v_mfma_f32_32x32x16_bf16 v[50:65], v[114:117], v[110:113], v[50:65]
	v_add_u32_e32 v0, 31, v75
	v_cmp_le_i32_e32 vcc, v0, v188
	v_add_u32_e32 v0, 47, v75
	s_mov_b64 s[30:31], -1
	s_nop 5
	v_cndmask_b32_e32 v34, v252, v34, vcc
	v_cmp_le_i32_e32 vcc, v0, v188
	v_add_u32_e32 v0, 63, v75
	s_nop 0
	v_cndmask_b32_e32 v35, v252, v35, vcc
	v_cmp_le_i32_e32 vcc, v0, v188
	v_add_u32_e32 v0, 0x9f, v75
	s_nop 0
	v_cndmask_b32_e32 v36, v252, v36, vcc
	v_cmp_le_i32_e32 vcc, v75, v144
	s_nop 1
	v_cndmask_b32_e32 v37, v252, v37, vcc
	v_cmp_le_i32_e32 vcc, v0, v188
	v_add_u32_e32 v0, 0xaf, v75
	s_nop 0
	v_cndmask_b32_e32 v38, v252, v38, vcc
	v_cmp_le_i32_e32 vcc, v0, v188
	v_add_u32_e32 v0, 0xbf, v75
	s_nop 0
	v_cndmask_b32_e32 v39, v252, v39, vcc
	v_cmp_le_i32_e32 vcc, v0, v188
	v_add_u32_e32 v0, 0x11f, v75
	s_nop 0
	v_cndmask_b32_e32 v40, v252, v40, vcc
	v_cmp_le_i32_e32 vcc, v75, v145
	s_nop 1
	v_cndmask_b32_e32 v41, v252, v41, vcc
	v_cmp_le_i32_e32 vcc, v0, v188
	v_add_u32_e32 v0, 0x12f, v75
	s_nop 0
	v_cndmask_b32_e32 v42, v252, v42, vcc
	v_cmp_le_i32_e32 vcc, v0, v188
	v_add_u32_e32 v0, 0x13f, v75
	s_nop 0
	v_cndmask_b32_e32 v43, v252, v43, vcc
	v_cmp_le_i32_e32 vcc, v0, v188
	v_add_u32_e32 v0, 0x19f, v75
	s_nop 0
	v_cndmask_b32_e32 v44, v252, v44, vcc
	v_cmp_le_i32_e32 vcc, v75, v146
	s_nop 1
	v_cndmask_b32_e32 v45, v252, v45, vcc
	v_cmp_le_i32_e32 vcc, v0, v188
	v_add_u32_e32 v0, 0x1af, v75
	s_nop 0
	v_cndmask_b32_e32 v46, v252, v46, vcc
	v_cmp_le_i32_e32 vcc, v0, v188
	v_add_u32_e32 v0, 0x1bf, v75
	s_nop 0
	v_cndmask_b32_e32 v47, v252, v47, vcc
	v_cmp_le_i32_e32 vcc, v0, v188
	v_add_u32_e32 v0, 0x21f, v75
	s_nop 0
	v_cndmask_b32_e32 v48, v252, v48, vcc
	v_cmp_le_i32_e32 vcc, v75, v147
	s_nop 1
	v_cndmask_b32_e32 v49, v252, v49, vcc
	v_cmp_le_i32_e32 vcc, v0, v188
	v_add_u32_e32 v0, 0x22f, v75
	s_nop 0
	v_cndmask_b32_e32 v50, v252, v50, vcc
	v_cmp_le_i32_e32 vcc, v0, v188
	v_add_u32_e32 v0, 0x23f, v75
	s_nop 0
	v_cndmask_b32_e32 v51, v252, v51, vcc
	v_cmp_le_i32_e32 vcc, v0, v188
	v_add_u32_e32 v0, 0x29f, v75
	s_nop 0
	v_cndmask_b32_e32 v52, v252, v52, vcc
	v_cmp_le_i32_e32 vcc, v75, v148
	s_nop 1
	v_cndmask_b32_e32 v53, v252, v53, vcc
	v_cmp_le_i32_e32 vcc, v0, v188
	v_add_u32_e32 v0, 0x2af, v75
	s_nop 0
	v_cndmask_b32_e32 v54, v252, v54, vcc
	v_cmp_le_i32_e32 vcc, v0, v188
	v_add_u32_e32 v0, 0x2bf, v75
	s_nop 0
	v_cndmask_b32_e32 v55, v252, v55, vcc
	v_cmp_le_i32_e32 vcc, v0, v188
	v_add_u32_e32 v0, 0x31f, v75
	s_nop 0
	v_cndmask_b32_e32 v56, v252, v56, vcc
	v_cmp_le_i32_e32 vcc, v75, v149
	s_nop 1
	v_cndmask_b32_e32 v57, v252, v57, vcc
	v_cmp_le_i32_e32 vcc, v0, v188
	v_add_u32_e32 v0, 0x32f, v75
	s_nop 0
	v_cndmask_b32_e32 v58, v252, v58, vcc
	v_cmp_le_i32_e32 vcc, v0, v188
	v_add_u32_e32 v0, 0x33f, v75
	s_nop 0
	v_cndmask_b32_e32 v59, v252, v59, vcc
	v_cmp_le_i32_e32 vcc, v0, v188
	v_add_u32_e32 v0, 0x39f, v75
	s_nop 0
	v_cndmask_b32_e32 v60, v252, v60, vcc
	v_cmp_le_i32_e32 vcc, v75, v150
	s_nop 1
	v_cndmask_b32_e32 v61, v252, v61, vcc
	v_cmp_le_i32_e32 vcc, v0, v188
	v_add_u32_e32 v0, 0x3af, v75
	s_nop 0
	v_cndmask_b32_e32 v62, v252, v62, vcc
	v_cmp_le_i32_e32 vcc, v0, v188
	v_add_u32_e32 v0, 0x3bf, v75
	s_nop 0
	v_cndmask_b32_e32 v63, v252, v63, vcc
	v_cmp_le_i32_e32 vcc, v0, v188
	s_nop 1
	v_cndmask_b32_e32 v64, v252, v64, vcc
	v_cmp_le_i32_e32 vcc, v75, v151
	s_nop 1
	v_cndmask_b32_e32 v65, v252, v65, vcc
	s_nop 15
	s_nop 7
	s_nop 0
	v_max3_f32 v0, v34, v35, v36
	v_max3_f32 v76, v50, v51, v52
	s_nop 0
	v_max3_f32 v0, v0, v37, v38
	v_max3_f32 v76, v76, v53, v54
	s_nop 0
	v_max3_f32 v0, v0, v39, v40
	v_max3_f32 v76, v76, v55, v56
	s_nop 0
	v_max3_f32 v0, v0, v41, v42
	v_max3_f32 v76, v76, v57, v58
	s_nop 0
	v_max3_f32 v0, v0, v43, v44
	v_max3_f32 v76, v76, v59, v60
	s_nop 0
	v_max3_f32 v0, v0, v45, v46
	v_max3_f32 v76, v76, v61, v62
	s_nop 0
	v_max3_f32 v0, v0, v47, v48
	v_max3_f32 v76, v76, v63, v64
	s_nop 0
	v_max3_f32 v0, v0, v49, v65
	s_nop 0
	v_max_f32 v0, v0, v76
	s_nop 0
	v_mov_b32_e32 v76, v0
	s_nop 1
	v_permlane32_swap_b32_e32 v0, v76
	v_max_f32_e32 v76, v76, v76
	v_max_f32_e32 v0, v0, v0
	v_max_f32_e32 v0, v0, v76
	v_cmp_lt_f32_e32 vcc, s60, v0
	v_cmp_lt_f32_e64 s[18:19], s61, v0
	s_andn2_b64 s[18:19], s[18:19], s[52:53]
	s_or_b64 s[30:31], vcc, s[18:19]
	s_mov_b64 s[18:19], s[52:53]
	s_cbranch_scc0 .LBB0_1072
; DI float fexp2(float x) { return __builtin_amdgcn_exp2f(x); }
; template <int DQK, int MODE, class Mask> ...
;     ...
;                     const float dl = need ? mt : 0.f;
;                     const float alpha = href ? fexp2(-dl) : 0.f;
;                     mref += dl; href = href || need;
; #pragma unroll
;                     for (int kb = 0; kb < 2; ++kb)
; #pragma unroll
;                         for (int i = 0; i < 16; ++i) s[kb][i] -= dl;
; #pragma unroll
;                     for (int i = 0; i < 16; ++i) { negm16[i] = -mref; ol[i] *= alpha; }
;                     if (MODE == 0) {
; #pragma unroll
;                         for (int d = 0; d < 2; ++d)
; #pragma unroll
;                             for (int i = 0; i < 16; ++i) o[d][i] *= alpha;
;                     }
;                 }
	v_cndmask_b32_e64 v18, 0, v0, s[30:31]
	v_exp_f32_e64 v0, -v18
	v_add_f32_e32 v74, v74, v18
	s_or_b64 s[30:31], s[52:53], s[30:31]
	v_sub_f32_e32 v34, v34, v18
	v_sub_f32_e32 v35, v35, v18
	v_sub_f32_e32 v36, v36, v18
	v_cndmask_b32_e64 v0, 0, v0, s[52:53]
	v_sub_f32_e32 v37, v37, v18
	v_sub_f32_e32 v38, v38, v18
	v_sub_f32_e32 v39, v39, v18
	v_sub_f32_e32 v40, v40, v18
	v_sub_f32_e32 v41, v41, v18
	v_sub_f32_e32 v42, v42, v18
	v_sub_f32_e32 v43, v43, v18
	v_sub_f32_e32 v44, v44, v18
	v_sub_f32_e32 v45, v45, v18
	v_sub_f32_e32 v46, v46, v18
	v_sub_f32_e32 v47, v47, v18
	v_sub_f32_e32 v48, v48, v18
	v_sub_f32_e32 v49, v49, v18
	v_sub_f32_e32 v50, v50, v18
	v_sub_f32_e32 v51, v51, v18
	v_sub_f32_e32 v52, v52, v18
	v_sub_f32_e32 v53, v53, v18
	v_sub_f32_e32 v54, v54, v18
	v_sub_f32_e32 v55, v55, v18
	v_sub_f32_e32 v56, v56, v18
	v_sub_f32_e32 v57, v57, v18
	v_sub_f32_e32 v58, v58, v18
	v_sub_f32_e32 v59, v59, v18
	v_sub_f32_e32 v60, v60, v18
	v_sub_f32_e32 v61, v61, v18
	v_sub_f32_e32 v62, v62, v18
	v_sub_f32_e32 v63, v63, v18
	v_sub_f32_e32 v64, v64, v18
	v_sub_f32_e32 v65, v65, v18
	v_xor_b32_e32 v18, 0x80000000, v74
	s_andn2_b64 s[18:19], s[18:19], exec
	s_and_b64 s[30:31], s[30:31], exec
	v_pk_mul_f32 v[16:17], v[16:17], v[0:1] op_sel_hi:[1,0]
	v_pk_mul_f32 v[14:15], v[14:15], v[0:1] op_sel_hi:[1,0]
	v_pk_mul_f32 v[12:13], v[12:13], v[0:1] op_sel_hi:[1,0]
	v_pk_mul_f32 v[10:11], v[10:11], v[0:1] op_sel_hi:[1,0]
	v_pk_mul_f32 v[8:9], v[8:9], v[0:1] op_sel_hi:[1,0]
	v_pk_mul_f32 v[6:7], v[6:7], v[0:1] op_sel_hi:[1,0]
	v_pk_mul_f32 v[4:5], v[4:5], v[0:1] op_sel_hi:[1,0]
	v_pk_mul_f32 v[2:3], v[2:3], v[0:1] op_sel_hi:[1,0]
	s_or_b64 s[52:53], s[18:19], s[30:31]
	v_mov_b32_e32 v19, v18
	v_mov_b32_e32 v20, v18
	v_mov_b32_e32 v21, v18
	v_mov_b32_e32 v22, v18
	v_mov_b32_e32 v23, v18
	v_mov_b32_e32 v24, v18
	v_mov_b32_e32 v25, v18
	v_mov_b32_e32 v26, v18
	v_mov_b32_e32 v27, v18
	v_mov_b32_e32 v28, v18
	v_mov_b32_e32 v29, v18
	v_mov_b32_e32 v30, v18
	v_mov_b32_e32 v31, v18
	v_mov_b32_e32 v32, v18
	v_mov_b32_e32 v33, v18
	s_branch .LBB0_1072

; DI float fexp2(float x) { return __builtin_amdgcn_exp2f(x); }
; template <int DQK, int MODE, class Mask> ...
;     ...
;                     const float dl = need ? mt : 0.f;
;                     const float alpha = href ? fexp2(-dl) : 0.f;
;                     mref += dl; href = href || need;
; #pragma unroll
;                     for (int kb = 0; kb < 2; ++kb)
; #pragma unroll
;                         for (int i = 0; i < 16; ++i) s[kb][i] -= dl;
; #pragma unroll
;                     for (int i = 0; i < 16; ++i) { negm16[i] = -mref; ol[i] *= alpha; }
;                     if (MODE == 0) {
; #pragma unroll
;                         for (int d = 0; d < 2; ++d)
; #pragma unroll
;                             for (int i = 0; i < 16; ++i) o[d][i] *= alpha;
;                     }
;                 }
.Ltrim_27890:
	v_cndmask_b32_e64 v50, 0, v0, s[20:21]
	v_exp_f32_e64 v0, -v50
	v_add_f32_e32 v183, v183, v50
	v_sub_f32_e32 v82, v82, v50
	v_sub_f32_e32 v83, v83, v50
	v_cndmask_b32_e64 v0, 0, v0, s[16:17]
	s_or_b64 s[16:17], s[16:17], s[20:21]
	v_sub_f32_e32 v84, v84, v50
	v_sub_f32_e32 v85, v85, v50
	v_sub_f32_e32 v86, v86, v50
	v_sub_f32_e32 v87, v87, v50
	v_sub_f32_e32 v88, v88, v50
	v_sub_f32_e32 v89, v89, v50
	v_sub_f32_e32 v90, v90, v50
	v_sub_f32_e32 v91, v91, v50
	v_sub_f32_e32 v92, v92, v50
	v_sub_f32_e32 v93, v93, v50
	v_sub_f32_e32 v94, v94, v50
	v_sub_f32_e32 v95, v95, v50
	v_sub_f32_e32 v96, v96, v50
	v_sub_f32_e32 v97, v97, v50
	v_sub_f32_e32 v66, v66, v50
	v_sub_f32_e32 v67, v67, v50
	v_sub_f32_e32 v68, v68, v50
	v_sub_f32_e32 v69, v69, v50
	v_sub_f32_e32 v70, v70, v50
	v_sub_f32_e32 v71, v71, v50
	v_sub_f32_e32 v72, v72, v50
	v_sub_f32_e32 v73, v73, v50
	v_sub_f32_e32 v74, v74, v50
	v_sub_f32_e32 v75, v75, v50
	v_sub_f32_e32 v76, v76, v50
	v_sub_f32_e32 v77, v77, v50
	v_sub_f32_e32 v78, v78, v50
	v_sub_f32_e32 v79, v79, v50
	v_sub_f32_e32 v80, v80, v50
	v_sub_f32_e32 v81, v81, v50
	v_xor_b32_e32 v50, 0x80000000, v183
	s_andn2_b64 s[20:21], s[30:31], exec
	s_and_b64 s[16:17], s[16:17], exec
	v_pk_mul_f32 v[48:49], v[48:49], v[0:1] op_sel_hi:[1,0]
	v_pk_mul_f32 v[46:47], v[46:47], v[0:1] op_sel_hi:[1,0]
	v_pk_mul_f32 v[44:45], v[44:45], v[0:1] op_sel_hi:[1,0]
	v_pk_mul_f32 v[42:43], v[42:43], v[0:1] op_sel_hi:[1,0]
	v_pk_mul_f32 v[40:41], v[40:41], v[0:1] op_sel_hi:[1,0]
	v_pk_mul_f32 v[38:39], v[38:39], v[0:1] op_sel_hi:[1,0]
	v_pk_mul_f32 v[36:37], v[36:37], v[0:1] op_sel_hi:[1,0]
	v_pk_mul_f32 v[34:35], v[34:35], v[0:1] op_sel_hi:[1,0]
	v_pk_mul_f32 v[16:17], v[16:17], v[0:1] op_sel_hi:[1,0]
	v_pk_mul_f32 v[14:15], v[14:15], v[0:1] op_sel_hi:[1,0]
	v_pk_mul_f32 v[12:13], v[12:13], v[0:1] op_sel_hi:[1,0]
	v_pk_mul_f32 v[10:11], v[10:11], v[0:1] op_sel_hi:[1,0]
	v_pk_mul_f32 v[8:9], v[8:9], v[0:1] op_sel_hi:[1,0]
	v_pk_mul_f32 v[6:7], v[6:7], v[0:1] op_sel_hi:[1,0]
	v_pk_mul_f32 v[4:5], v[4:5], v[0:1] op_sel_hi:[1,0]
	v_pk_mul_f32 v[2:3], v[2:3], v[0:1] op_sel_hi:[1,0]
	v_pk_mul_f32 v[32:33], v[32:33], v[0:1] op_sel_hi:[1,0]
	v_pk_mul_f32 v[30:31], v[30:31], v[0:1] op_sel_hi:[1,0]
	v_pk_mul_f32 v[28:29], v[28:29], v[0:1] op_sel_hi:[1,0]
	v_pk_mul_f32 v[26:27], v[26:27], v[0:1] op_sel_hi:[1,0]
	v_pk_mul_f32 v[24:25], v[24:25], v[0:1] op_sel_hi:[1,0]
	v_pk_mul_f32 v[22:23], v[22:23], v[0:1] op_sel_hi:[1,0]
	v_pk_mul_f32 v[20:21], v[20:21], v[0:1] op_sel_hi:[1,0]
	v_pk_mul_f32 v[18:19], v[18:19], v[0:1] op_sel_hi:[1,0]
	s_or_b64 s[16:17], s[20:21], s[16:17]
	v_mov_b32_e32 v51, v50
	v_mov_b32_e32 v52, v50
	v_mov_b32_e32 v53, v50
	v_mov_b32_e32 v54, v50
	v_mov_b32_e32 v55, v50
	v_mov_b32_e32 v56, v50
	v_mov_b32_e32 v57, v50
	v_mov_b32_e32 v58, v50
	v_mov_b32_e32 v59, v50
	v_mov_b32_e32 v60, v50
	v_mov_b32_e32 v61, v50
	v_mov_b32_e32 v62, v50
	v_mov_b32_e32 v63, v50
	v_mov_b32_e32 v64, v50
	v_mov_b32_e32 v65, v50

; template <int DQK, int MODE, class Mask> ...
;     ...
;                 for (int kk = 0; kk < NKS; ++kk) kf[kb][kk] = *(const LAS bf16x8*)(Ks + (32 * kb + r) * KP + (16 * kk + 8 * h) * 2);
;             __builtin_amdgcn_sched_barrier(0);
;             f32x16 s[2];
;             asm volatile("v_mfma_f32_32x32x16_bf16 %0, %1, %2, %3" : "=&v"(s[0]) : "v"(kf[0][0]), "v"(qf[0]), "v"(negm16));
;             asm volatile("v_mfma_f32_32x32x16_bf16 %0, %1, %2, %3" : "=&v"(s[1]) : "v"(kf[1][0]), "v"(qf[0]), "v"(negm16));
; #pragma unroll
;             for (int kk = 1; kk < NKS; ++kk) {
;                 s[0] = MFMA32(kf[0][kk], qf[kk], s[0]);
;                 s[1] = MFMA32(kf[1][kk], qf[kk], s[1]);
;             }
;             __builtin_amdgcn_sched_barrier(0);
;             s16x4 vlo[2][2][2], vhi[2][2][2];
;             if (MODE != 1) {
;                 const int q4 = (lane & 15) >> 2, p4 = lane & 3, blk = (lane >> 4) & 1;
;                 const LAS char* vb0 = Vs + (4 * h + q4) * VP + (16 * blk) * 2 + 8 * p4;
; #pragma unroll
;                 for (int kb = 0; kb < 2; ++kb)
; #pragma unroll
;                     for (int s2 = 0; s2 < 2; ++s2)
; #pragma unroll
;                         for (int d = 0; d < 2; ++d) { const LAS char* vb = vb0 + (32 * kb + 16 * s2) * VP + (32 * d) * 2; vlo[kb][s2][d] = vtr(vb); vhi[kb][s2][d] = vtr(vb + 8 * VP); }
;             }
;             __builtin_amdgcn_sched_barrier(0);
;             const int key0 = j * 64 + 4 * h;
;             if (mask.needs(j)) {
; #pragma unroll
;                 for (int kb = 0; kb < 2; ++kb)
; #pragma unroll
;                     for (int i = 0; i < 16; ++i) { const int key = key0 + 32 * kb + (i & 3) + 8 * (i >> 2); s[kb][i] = mask(key, j) ? s[kb][i] : -3e30f; }
;             }
;             const bool on = mask.lane_on(j);
;             if (MODE == 0 || MODE == 1) {
;                 asm volatile("s_nop 15\n\ts_nop 7" : "+v"(s[0]), "+v"(s[1]));
;                 float mt, mu;
;                 asm volatile("v_max3_f32 %0, %1, %2, %3" : "=v"(mt) : "v"(s[0][0]), "v"(s[0][1]), "v"(s[0][2]));
;                 asm volatile("v_max3_f32 %0, %1, %2, %3" : "=v"(mu) : "v"(s[1][0]), "v"(s[1][1]), "v"(s[1][2]));
; #pragma unroll
;                 for (int i = 3; i < 15; i += 2) {
;                     asm volatile("v_max3_f32 %0, %1, %2, %3" : "=v"(mt) : "v"(mt), "v"(s[0][i]), "v"(s[0][i + 1]));
.LBB0_1099:
	s_mul_i32 s13, s12, 0x3400
	v_add_u32_e32 v0, s13, v219
	v_add_u32_e32 v70, v0, v224
	v_add_u32_e32 v0, v0, v225
	ds_read_b128 v[66:69], v70
	ds_read_b128 v[122:125], v70 offset:32
	ds_read_b128 v[126:129], v70 offset:64
	ds_read_b128 v[204:207], v70 offset:96
	ds_read_b128 v[130:133], v0
	ds_read_b128 v[134:137], v0 offset:32
	ds_read_b128 v[138:141], v0 offset:64
	ds_read_b128 v[142:145], v0 offset:96
	s_waitcnt lgkmcnt(7)
	v_mfma_f32_32x32x16_bf16 v[82:97], v[66:69], v[98:101], v[50:65]
	s_waitcnt lgkmcnt(3)
	v_mfma_f32_32x32x16_bf16 v[66:81], v[130:133], v[98:101], v[50:65]
	s_mulk_i32 s12, 0x2400
	s_waitcnt lgkmcnt(2)
	v_mfma_f32_32x32x16_bf16 v[66:81], v[134:137], v[102:105], v[66:81]
	s_waitcnt lgkmcnt(1)
	v_mfma_f32_32x32x16_bf16 v[66:81], v[138:141], v[106:109], v[66:81]
	s_waitcnt lgkmcnt(0)
	v_mfma_f32_32x32x16_bf16 v[66:81], v[142:145], v[110:113], v[66:81]
	v_mfma_f32_32x32x16_bf16 v[82:97], v[122:125], v[102:105], v[82:97]
	v_add_u32_e32 v0, s12, v228
	ds_read_b64_tr_b16 v[150:151], v0 offset:26624
	ds_read_b64_tr_b16 v[152:153], v0 offset:27776
	ds_read_b64_tr_b16 v[148:149], v0 offset:27840
	ds_read_b64_tr_b16 v[146:147], v0 offset:26688
	ds_read_b64_tr_b16 v[142:143], v0 offset:28928
	ds_read_b64_tr_b16 v[144:145], v0 offset:30080
	ds_read_b64_tr_b16 v[140:141], v0 offset:30144
	ds_read_b64_tr_b16 v[138:139], v0 offset:28992
	v_mfma_f32_32x32x16_bf16 v[82:97], v[126:129], v[106:109], v[82:97]
	ds_read_b64_tr_b16 v[134:135], v0 offset:31232
	ds_read_b64_tr_b16 v[136:137], v0 offset:32384
	ds_read_b64_tr_b16 v[132:133], v0 offset:32448
	ds_read_b64_tr_b16 v[130:131], v0 offset:31296
	ds_read_b64_tr_b16 v[126:127], v0 offset:33536
	ds_read_b64_tr_b16 v[128:129], v0 offset:34688
	ds_read_b64_tr_b16 v[124:125], v0 offset:34752
	ds_read_b64_tr_b16 v[122:123], v0 offset:33600
	v_mfma_f32_32x32x16_bf16 v[82:97], v[204:207], v[110:113], v[82:97]
	s_nop 15
	s_nop 7
	v_lshrrev_b64 v[204:205], s18, v[190:191]
	v_max3_f32 v0, v82, v83, v84
	v_max3_f32 v189, v66, v67, v68
	s_mov_b64 s[20:21], -1
	v_max3_f32 v0, v0, v85, v86
	v_max3_f32 v189, v189, v69, v70
	s_nop 0
	v_max3_f32 v0, v0, v87, v88
	v_max3_f32 v189, v189, v71, v72
	s_nop 0
	v_max3_f32 v0, v0, v89, v90
	v_max3_f32 v189, v189, v73, v74
	s_nop 0
	v_max3_f32 v0, v0, v91, v92
	v_max3_f32 v189, v189, v75, v76
	s_nop 0
	v_max3_f32 v0, v0, v93, v94
	v_max3_f32 v189, v189, v77, v78
	s_nop 0
	v_max3_f32 v206, v0, v95, v96
	v_and_b32_e32 v0, 1, v204
	v_max3_f32 v189, v189, v79, v80
	v_cmp_eq_u64_e64 s[12:13], 0, v[0:1]
	v_max3_f32 v204, v206, v97, v81
	s_nop 0
	v_max_f32 v189, v204, v189
	s_nop 0
	v_cndmask_b32_e64 v0, v189, v252, s[12:13]
	v_mov_b32_e32 v189, v0
	s_nop 1
	v_permlane32_swap_b32_e32 v0, v189
	v_max_f32_e32 v189, v189, v189
	v_max_f32_e32 v0, v0, v0
	v_max_f32_e32 v0, v0, v189
	v_cmp_lt_f32_e32 vcc, s60, v0
	v_cmp_lt_f32_e64 s[30:31], s61, v0
	s_andn2_b64 s[30:31], s[30:31], s[16:17]
	s_or_b64 s[20:21], vcc, s[30:31]
	s_mov_b64 s[30:31], s[16:17]
	s_cbranch_scc0 .LBB0_1096
	s_branch .Ltrim_27890

; DI float fexp2(float x) { return __builtin_amdgcn_exp2f(x); }
; DI float xhalf_max(float v) { auto rr = __builtin_amdgcn_permlane32_swap(__float_as_uint(v), __float_as_uint(v), false, false); return fmaxf(__uint_as_float(rr[0]), __uint_as_float(rr[1])); }
; template <int DQK, int MODE, class Mask> ...
;     ...
;                 asm volatile("s_nop 15\n\ts_nop 7" : "+v"(s[0]), "+v"(s[1]));
;                 float mt, mu;
;                 asm volatile("v_max3_f32 %0, %1, %2, %3" : "=v"(mt) : "v"(s[0][0]), "v"(s[0][1]), "v"(s[0][2]));
;                 asm volatile("v_max3_f32 %0, %1, %2, %3" : "=v"(mu) : "v"(s[1][0]), "v"(s[1][1]), "v"(s[1][2]));
; #pragma unroll
;                 for (int i = 3; i < 15; i += 2) {
;                     asm volatile("v_max3_f32 %0, %1, %2, %3" : "=v"(mt) : "v"(mt), "v"(s[0][i]), "v"(s[0][i + 1]));
;                     asm volatile("v_max3_f32 %0, %1, %2, %3" : "=v"(mu) : "v"(mu), "v"(s[1][i]), "v"(s[1][i + 1]));
;                 }
;                 asm volatile("v_max3_f32 %0, %1, %2, %3" : "=v"(mt) : "v"(mt), "v"(s[0][15]), "v"(s[1][15]));
;                 asm volatile("v_max_f32 %0, %1, %2" : "=v"(mt) : "v"(mt), "v"(mu));
;                 mt = on ? mt : -3e30f;
;                 mt = xhalf_max(mt);
;                 const bool need = (mt > 8.0f) || (!href && mt > -1e29f);
;                 if (__builtin_amdgcn_ballot_w64(need) != 0ull) {
;                     const float dl = need ? mt : 0.f;
;                     const float alpha = href ? fexp2(-dl) : 0.f;
;                     mref += dl; href = href || need;
; #pragma unroll
;                     for (int kb = 0; kb < 2; ++kb)
; #pragma unroll
;                         for (int i = 0; i < 16; ++i) s[kb][i] -= dl;
; #pragma unroll
;                     for (int i = 0; i < 16; ++i) { negm16[i] = -mref; ol[i] *= alpha; }
;                     if (MODE == 0) {
; #pragma unroll
;                         for (int d = 0; d < 2; ++d)
; #pragma unroll
;                             for (int i = 0; i < 16; ++i) o[d][i] *= alpha;
;                     }
;                 }
.LBB0_1107:
	s_nop 15
	s_nop 7
	s_mov_b64 s[18:19], -1
	v_max3_f32 v0, v82, v83, v84
	v_max3_f32 v130, v66, v67, v68
	s_nop 0
	v_max3_f32 v0, v0, v85, v86
	v_max3_f32 v130, v130, v69, v70
	s_nop 0
	v_max3_f32 v0, v0, v87, v88
	v_max3_f32 v130, v130, v71, v72
	s_nop 0
	v_max3_f32 v0, v0, v89, v90
	v_max3_f32 v130, v130, v73, v74
	s_nop 0
	v_max3_f32 v0, v0, v91, v92
	v_max3_f32 v130, v130, v75, v76
	s_nop 0
	v_max3_f32 v0, v0, v93, v94
	v_max3_f32 v130, v130, v77, v78
	s_nop 0
	v_max3_f32 v132, v0, v95, v96
	v_max3_f32 v133, v130, v79, v80
	v_lshrrev_b64 v[130:131], s12, v[190:191]
	v_and_b32_e32 v0, 1, v130
	v_max3_f32 v130, v132, v97, v81
	v_cmp_eq_u64_e64 s[12:13], 0, v[0:1]
	v_max_f32 v130, v130, v133
	s_nop 1
	v_cndmask_b32_e64 v0, v130, v252, s[12:13]
	v_mov_b32_e32 v130, v0
	s_nop 1
	v_permlane32_swap_b32_e32 v0, v130
	v_max_f32_e32 v130, v130, v130
	v_max_f32_e32 v0, v0, v0
	v_max_f32_e32 v0, v0, v130
	v_cmp_lt_f32_e32 vcc, s60, v0
	v_cmp_lt_f32_e64 s[20:21], s61, v0
	s_andn2_b64 s[20:21], s[20:21], s[16:17]
	s_or_b64 s[18:19], vcc, s[20:21]
	s_cbranch_scc0 .LBB0_1111
	v_cndmask_b32_e64 v130, 0, v0, s[18:19]
	v_exp_f32_e64 v0, -v130
	v_sub_f32_e32 v82, v82, v130
	v_sub_f32_e32 v83, v83, v130
	v_sub_f32_e32 v84, v84, v130
	v_cndmask_b32_e64 v0, 0, v0, s[16:17]
	v_sub_f32_e32 v85, v85, v130
	v_sub_f32_e32 v86, v86, v130
	v_sub_f32_e32 v87, v87, v130
	v_sub_f32_e32 v88, v88, v130
	v_sub_f32_e32 v89, v89, v130
	v_sub_f32_e32 v90, v90, v130
	v_sub_f32_e32 v91, v91, v130
	v_sub_f32_e32 v92, v92, v130
	v_sub_f32_e32 v93, v93, v130
	v_sub_f32_e32 v94, v94, v130
	v_sub_f32_e32 v95, v95, v130
	v_sub_f32_e32 v96, v96, v130
	v_sub_f32_e32 v97, v97, v130
	v_sub_f32_e32 v66, v66, v130
	v_sub_f32_e32 v67, v67, v130
	v_sub_f32_e32 v68, v68, v130
	v_sub_f32_e32 v69, v69, v130
	v_sub_f32_e32 v70, v70, v130
	v_sub_f32_e32 v71, v71, v130
	v_sub_f32_e32 v72, v72, v130
	v_sub_f32_e32 v73, v73, v130
	v_sub_f32_e32 v74, v74, v130
	v_sub_f32_e32 v75, v75, v130
	v_sub_f32_e32 v76, v76, v130
	v_sub_f32_e32 v77, v77, v130
	v_sub_f32_e32 v78, v78, v130
	v_sub_f32_e32 v79, v79, v130
	v_sub_f32_e32 v80, v80, v130
	v_sub_f32_e32 v81, v81, v130
	v_pk_mul_f32 v[48:49], v[48:49], v[0:1] op_sel_hi:[1,0]
	v_pk_mul_f32 v[46:47], v[46:47], v[0:1] op_sel_hi:[1,0]
	v_pk_mul_f32 v[44:45], v[44:45], v[0:1] op_sel_hi:[1,0]
	v_pk_mul_f32 v[42:43], v[42:43], v[0:1] op_sel_hi:[1,0]
	v_pk_mul_f32 v[40:41], v[40:41], v[0:1] op_sel_hi:[1,0]
	v_pk_mul_f32 v[38:39], v[38:39], v[0:1] op_sel_hi:[1,0]
	v_pk_mul_f32 v[36:37], v[36:37], v[0:1] op_sel_hi:[1,0]
	v_pk_mul_f32 v[34:35], v[34:35], v[0:1] op_sel_hi:[1,0]
	v_pk_mul_f32 v[16:17], v[16:17], v[0:1] op_sel_hi:[1,0]
	v_pk_mul_f32 v[14:15], v[14:15], v[0:1] op_sel_hi:[1,0]
	v_pk_mul_f32 v[12:13], v[12:13], v[0:1] op_sel_hi:[1,0]
	v_pk_mul_f32 v[10:11], v[10:11], v[0:1] op_sel_hi:[1,0]
	v_pk_mul_f32 v[8:9], v[8:9], v[0:1] op_sel_hi:[1,0]
	v_pk_mul_f32 v[6:7], v[6:7], v[0:1] op_sel_hi:[1,0]
	v_pk_mul_f32 v[4:5], v[4:5], v[0:1] op_sel_hi:[1,0]
	v_pk_mul_f32 v[2:3], v[2:3], v[0:1] op_sel_hi:[1,0]
	v_pk_mul_f32 v[32:33], v[32:33], v[0:1] op_sel_hi:[1,0]
	v_pk_mul_f32 v[30:31], v[30:31], v[0:1] op_sel_hi:[1,0]
	v_pk_mul_f32 v[28:29], v[28:29], v[0:1] op_sel_hi:[1,0]
	v_pk_mul_f32 v[26:27], v[26:27], v[0:1] op_sel_hi:[1,0]
	v_pk_mul_f32 v[24:25], v[24:25], v[0:1] op_sel_hi:[1,0]
	v_pk_mul_f32 v[22:23], v[22:23], v[0:1] op_sel_hi:[1,0]
	v_pk_mul_f32 v[20:21], v[20:21], v[0:1] op_sel_hi:[1,0]
	v_pk_mul_f32 v[18:19], v[18:19], v[0:1] op_sel_hi:[1,0]

; DI float fexp2(float x) { return __builtin_amdgcn_exp2f(x); }
; DI float xhalf_max(float v) { auto rr = __builtin_amdgcn_permlane32_swap(__float_as_uint(v), __float_as_uint(v), false, false); return fmaxf(__uint_as_float(rr[0]), __uint_as_float(rr[1])); }
; template <int DQK, int MODE, class Mask> ...
;     ...
;                 asm volatile("s_nop 15\n\ts_nop 7" : "+v"(s[0]), "+v"(s[1]));
;                 float mt, mu;
;                 asm volatile("v_max3_f32 %0, %1, %2, %3" : "=v"(mt) : "v"(s[0][0]), "v"(s[0][1]), "v"(s[0][2]));
;                 asm volatile("v_max3_f32 %0, %1, %2, %3" : "=v"(mu) : "v"(s[1][0]), "v"(s[1][1]), "v"(s[1][2]));
; #pragma unroll
;                 for (int i = 3; i < 15; i += 2) {
;                     asm volatile("v_max3_f32 %0, %1, %2, %3" : "=v"(mt) : "v"(mt), "v"(s[0][i]), "v"(s[0][i + 1]));
;                     asm volatile("v_max3_f32 %0, %1, %2, %3" : "=v"(mu) : "v"(mu), "v"(s[1][i]), "v"(s[1][i + 1]));
;                 }
;                 asm volatile("v_max3_f32 %0, %1, %2, %3" : "=v"(mt) : "v"(mt), "v"(s[0][15]), "v"(s[1][15]));
;                 asm volatile("v_max_f32 %0, %1, %2" : "=v"(mt) : "v"(mt), "v"(mu));
;                 mt = on ? mt : -3e30f;
;                 mt = xhalf_max(mt);
;                 const bool need = (mt > 8.0f) || (!href && mt > -1e29f);
;                 if (__builtin_amdgcn_ballot_w64(need) != 0ull) {
;                     const float dl = need ? mt : 0.f;
;                     const float alpha = href ? fexp2(-dl) : 0.f;
;                     mref += dl; href = href || need;
; #pragma unroll
;                     for (int kb = 0; kb < 2; ++kb)
; #pragma unroll
;                         for (int i = 0; i < 16; ++i) s[kb][i] -= dl;
; #pragma unroll
;                     for (int i = 0; i < 16; ++i) { negm16[i] = -mref; ol[i] *= alpha; }
;                     if (MODE == 0) {
; #pragma unroll
;                         for (int d = 0; d < 2; ++d)
; #pragma unroll
;                             for (int i = 0; i < 16; ++i) o[d][i] *= alpha;
;                     }
;                 }
.LBB0_1124:
	s_nop 15
	s_nop 7
	s_mov_b64 s[16:17], -1
	v_max3_f32 v0, v82, v83, v84
	v_max3_f32 v212, v66, v67, v68
	s_nop 0
	v_max3_f32 v0, v0, v85, v86
	v_max3_f32 v212, v212, v69, v70
	s_nop 0
	v_max3_f32 v0, v0, v87, v88
	v_max3_f32 v212, v212, v71, v72
	s_nop 0
	v_max3_f32 v0, v0, v89, v90
	v_max3_f32 v212, v212, v73, v74
	s_nop 0
	v_max3_f32 v0, v0, v91, v92
	v_max3_f32 v212, v212, v75, v76
	s_nop 0
	v_max3_f32 v0, v0, v93, v94
	v_max3_f32 v212, v212, v77, v78
	s_nop 0
	v_max3_f32 v0, v0, v95, v96
	v_max3_f32 v212, v212, v79, v80
	s_nop 0
	v_max3_f32 v0, v0, v97, v81
	s_nop 0
	v_max_f32 v0, v0, v212
	s_nop 0
	v_mov_b32_e32 v212, v0
	s_nop 1
	v_permlane32_swap_b32_e32 v0, v212
	v_max_f32_e32 v212, v212, v212
	v_max_f32_e32 v0, v0, v0
	v_max_f32_e32 v0, v0, v212
	v_cmp_lt_f32_e32 vcc, s60, v0
	v_cmp_lt_f32_e64 s[18:19], s61, v0
	s_andn2_b64 s[18:19], s[18:19], s[12:13]
	s_or_b64 s[16:17], vcc, s[18:19]
	s_cbranch_scc0 .LBB0_1115
	v_cndmask_b32_e64 v50, 0, v0, s[16:17]
	v_exp_f32_e64 v0, -v50
	v_add_f32_e32 v210, v210, v50
	s_or_b64 s[16:17], s[12:13], s[16:17]
	v_sub_f32_e32 v82, v82, v50
	v_sub_f32_e32 v83, v83, v50
	v_sub_f32_e32 v84, v84, v50
	v_cndmask_b32_e64 v0, 0, v0, s[12:13]
	v_sub_f32_e32 v85, v85, v50
	v_sub_f32_e32 v86, v86, v50
	v_sub_f32_e32 v87, v87, v50
	v_sub_f32_e32 v88, v88, v50
	v_sub_f32_e32 v89, v89, v50
	v_sub_f32_e32 v90, v90, v50
	v_sub_f32_e32 v91, v91, v50
	v_sub_f32_e32 v92, v92, v50
	v_sub_f32_e32 v93, v93, v50
	v_sub_f32_e32 v94, v94, v50
	v_sub_f32_e32 v95, v95, v50
	v_sub_f32_e32 v96, v96, v50
	v_sub_f32_e32 v97, v97, v50
	v_sub_f32_e32 v66, v66, v50
	v_sub_f32_e32 v67, v67, v50
	v_sub_f32_e32 v68, v68, v50
	v_sub_f32_e32 v69, v69, v50
	v_sub_f32_e32 v70, v70, v50
	v_sub_f32_e32 v71, v71, v50
	v_sub_f32_e32 v72, v72, v50
	v_sub_f32_e32 v73, v73, v50
	v_sub_f32_e32 v74, v74, v50
	v_sub_f32_e32 v75, v75, v50
	v_sub_f32_e32 v76, v76, v50
	v_sub_f32_e32 v77, v77, v50
	v_sub_f32_e32 v78, v78, v50
	v_sub_f32_e32 v79, v79, v50
	v_sub_f32_e32 v80, v80, v50
	v_sub_f32_e32 v81, v81, v50
	v_xor_b32_e32 v50, 0x80000000, v210
	s_andn2_b64 s[12:13], s[12:13], exec
	s_and_b64 s[16:17], s[16:17], exec
	v_pk_mul_f32 v[48:49], v[48:49], v[0:1] op_sel_hi:[1,0]
	v_pk_mul_f32 v[46:47], v[46:47], v[0:1] op_sel_hi:[1,0]
	v_pk_mul_f32 v[44:45], v[44:45], v[0:1] op_sel_hi:[1,0]
	v_pk_mul_f32 v[42:43], v[42:43], v[0:1] op_sel_hi:[1,0]
	v_pk_mul_f32 v[40:41], v[40:41], v[0:1] op_sel_hi:[1,0]
	v_pk_mul_f32 v[38:39], v[38:39], v[0:1] op_sel_hi:[1,0]
	v_pk_mul_f32 v[36:37], v[36:37], v[0:1] op_sel_hi:[1,0]
	v_pk_mul_f32 v[34:35], v[34:35], v[0:1] op_sel_hi:[1,0]
	v_pk_mul_f32 v[16:17], v[16:17], v[0:1] op_sel_hi:[1,0]
	v_pk_mul_f32 v[14:15], v[14:15], v[0:1] op_sel_hi:[1,0]
	v_pk_mul_f32 v[12:13], v[12:13], v[0:1] op_sel_hi:[1,0]
	v_pk_mul_f32 v[10:11], v[10:11], v[0:1] op_sel_hi:[1,0]
	v_pk_mul_f32 v[8:9], v[8:9], v[0:1] op_sel_hi:[1,0]
	v_pk_mul_f32 v[6:7], v[6:7], v[0:1] op_sel_hi:[1,0]
	v_pk_mul_f32 v[4:5], v[4:5], v[0:1] op_sel_hi:[1,0]
	v_pk_mul_f32 v[2:3], v[2:3], v[0:1] op_sel_hi:[1,0]
	v_pk_mul_f32 v[32:33], v[32:33], v[0:1] op_sel_hi:[1,0]
	v_pk_mul_f32 v[30:31], v[30:31], v[0:1] op_sel_hi:[1,0]
	v_pk_mul_f32 v[28:29], v[28:29], v[0:1] op_sel_hi:[1,0]
	v_pk_mul_f32 v[26:27], v[26:27], v[0:1] op_sel_hi:[1,0]
	v_pk_mul_f32 v[24:25], v[24:25], v[0:1] op_sel_hi:[1,0]
	v_pk_mul_f32 v[22:23], v[22:23], v[0:1] op_sel_hi:[1,0]
	v_pk_mul_f32 v[20:21], v[20:21], v[0:1] op_sel_hi:[1,0]
	v_pk_mul_f32 v[18:19], v[18:19], v[0:1] op_sel_hi:[1,0]
	s_or_b64 s[12:13], s[12:13], s[16:17]
	v_mov_b32_e32 v51, v50
	v_mov_b32_e32 v52, v50
	v_mov_b32_e32 v53, v50
	v_mov_b32_e32 v54, v50
	v_mov_b32_e32 v55, v50
	v_mov_b32_e32 v56, v50
	v_mov_b32_e32 v57, v50
	v_mov_b32_e32 v58, v50
	v_mov_b32_e32 v59, v50
	v_mov_b32_e32 v60, v50
	v_mov_b32_e32 v61, v50
	v_mov_b32_e32 v62, v50
	v_mov_b32_e32 v63, v50
	v_mov_b32_e32 v64, v50
	v_mov_b32_e32 v65, v50
	s_branch .LBB0_1115
